# placement: whole instruction stream shifted by 4 bytes (one s_nop 0 at entry) on top of the late stagger barrier
# speedup vs baseline: 1.0035x; 1.0006x over previous
_Z10fwd_kernel6Params:
	s_nop 0
	v_writelane_b32 v255, 0, 53
	s_mov_b64 s[78:79], s[0:1]
	s_load_dwordx4 s[88:91], s[0:1], 0x100
	s_nop 0
	s_load_dwordx2 s[0:1], s[0:1], 0x110
	v_and_b32_e32 v204, 0x3ff, v0
	s_mov_b32 s80, s2
	v_cmp_gt_u32_e32 vcc, 2, v204
	s_waitcnt lgkmcnt(0)
	v_writelane_b32 v254, s0, 0
	s_nop 1
	v_writelane_b32 v254, s1, 1
	s_and_saveexec_b64 s[0:1], vcc
	v_lshl_add_u32 v1, v204, 2, 0
	v_add_u32_e32 v1, 0x23fc0, v1
	v_mov_b32_e32 v2, 0
	ds_write_b32 v1, v2
	s_or_b64 exec, exec, s[0:1]
	s_load_dwordx2 s[2:3], s[78:79], 0x110
	s_waitcnt lgkmcnt(0)
	s_barrier
	s_sub_i32 s0, s3, s2
	s_cmp_lt_i32 s0, 2
	s_mov_b32 s0, 0
	v_writelane_b32 v254, s0, 2
	s_cbranch_scc1 .LBB0_7
	s_getreg_b32 s0, hwreg(HW_REG_XCC_ID, 0, 4)
	s_and_b32 s0, s0, 15
	v_writelane_b32 v254, s0, 2
	v_cmp_eq_u32_e32 vcc, 0, v204
	s_and_saveexec_b64 s[0:1], vcc
	s_cbranch_execz .LBB0_6
	s_mov_b64 s[2:3], exec
	v_mbcnt_lo_u32_b32 v1, s2, 0
	v_mbcnt_hi_u32_b32 v1, s3, v1
	v_cmp_eq_u32_e32 vcc, 0, v1
	s_and_b64 s[4:5], exec, vcc
	s_mov_b64 exec, s[4:5]
	s_cbranch_execz .LBB0_6
	v_readlane_b32 s4, v254, 2
	s_lshl_b32 s4, s4, 8
	s_bcnt1_i32_b64 s2, s[2:3]
	v_mov_b32_e32 v1, s4
	v_mov_b32_e32 v2, s2
	global_atomic_add v1, v2, s[90:91] offset:1024
